# attn0 plain loop: QK^T MFMA chain merged with softmax-finish VALU stream (K frags in free regs)
# speedup vs baseline: 1.0018x; 1.0018x over previous
.LBB0_309:
	s_mov_b32 s77, s74
	v_add3_u32 v215, s77, v209, v208
	v_add3_u32 v216, s77, v210, v208
	v_add3_u32 v233, s77, v211, v208
	v_add3_u32 v254, s77, v212, v208
	ds_read_b128 v[234:237], v215 offset:49152
	ds_read_b128 v[238:241], v215 offset:57344
	ds_read_b128 v[242:245], v216 offset:49152
	ds_read_b128 v[246:249], v216 offset:57344
	ds_read_b128 v[250:253], v233 offset:49152
	s_add_u32 s4, s70, 0xffffc000
	s_mov_b32 s74, s72
	s_addc_u32 s5, s71, -1
	s_add_i32 s72, s72, s42
	s_mov_b32 s73, m0
	s_mov_b32 m0, s72
	s_nop 0
	global_load_lds_dwordx4 v197, s[4:5]
	s_mov_b32 m0, s73
	s_addk_i32 s72, 0x400
	s_mov_b32 s73, m0
	s_mov_b32 m0, s72
	s_nop 0
	global_load_lds_dwordx4 v198, s[4:5]
	s_mov_b32 m0, s73
	s_add_i32 s4, s69, s97
	s_mov_b32 s5, m0
	s_mov_b32 m0, s4
	s_nop 0
	global_load_lds_dwordx4 v199, s[56:57]
	s_mov_b32 m0, s5
	s_addk_i32 s4, 0x400
	s_mov_b32 s5, m0
	s_mov_b32 m0, s4
	s_nop 0
	global_load_lds_dwordx4 v200, s[56:57]
	s_mov_b32 m0, s5
	s_setprio 1
	s_waitcnt lgkmcnt(4)
	v_mfma_f32_32x32x16_bf16 v[112:127], v[234:237], v[188:191], 0
	ds_read_b128 v[234:237], v233 offset:57344
	v_add_f32_e32 v1, 0, v230
	v_add_f32_e32 v1, v232, v1
	v_add_f32_e32 v1, v228, v1
	v_add_f32_e32 v1, v231, v1
	v_add_f32_e32 v1, v226, v1
	v_add_f32_e32 v1, v229, v1
	s_waitcnt lgkmcnt(4)
	v_mfma_f32_32x32x16_bf16 v[96:111], v[238:241], v[188:191], 0
	ds_read_b128 v[238:241], v254 offset:49152
	v_add_f32_e32 v1, v225, v1
	v_add_f32_e32 v1, v227, v1
	v_add_f32_e32 v1, v222, v1
	v_add_f32_e32 v1, v224, v1
	v_add_f32_e32 v1, v220, v1
	s_waitcnt lgkmcnt(4)
	v_mfma_f32_32x32x16_bf16 v[112:127], v[242:245], v[184:187], v[112:127]
	ds_read_b128 v[242:245], v254 offset:57344
	v_add_f32_e32 v1, v223, v1
	v_exp_f32_e32 v2, v128
	v_add_f32_e32 v1, v218, v1
	v_exp_f32_e32 v12, v129
	s_waitcnt lgkmcnt(4)
	v_mfma_f32_32x32x16_bf16 v[96:111], v[246:249], v[184:187], v[96:111]
	ds_read_b128 v[246:249], v215 offset:49280
	v_add_f32_e32 v1, v221, v1
	v_exp_f32_e32 v13, v130
	v_add_f32_e32 v1, v217, v1
	v_exp_f32_e32 v14, v131
	s_waitcnt lgkmcnt(4)
	v_mfma_f32_32x32x16_bf16 v[112:127], v[250:253], v[180:183], v[112:127]
	ds_read_b128 v[250:253], v215 offset:57472
	v_add_f32_e32 v1, v219, v1
	v_exp_f32_e32 v15, v132
	v_add_f32_e32 v1, v2, v1
	v_exp_f32_e32 v18, v133
	s_waitcnt lgkmcnt(4)
	v_mfma_f32_32x32x16_bf16 v[96:111], v[234:237], v[180:183], v[96:111]
	ds_read_b128 v[234:237], v216 offset:49280
	v_add_f32_e32 v1, v12, v1
	v_exp_f32_e32 v19, v134
	v_add_f32_e32 v1, v13, v1
	s_waitcnt lgkmcnt(4)
	v_mfma_f32_32x32x16_bf16 v[112:127], v[238:241], v[176:179], v[112:127]
	ds_read_b128 v[238:241], v216 offset:57472
	v_exp_f32_e32 v20, v135
	v_add_f32_e32 v1, v14, v1
	v_exp_f32_e32 v21, v136
	v_add_f32_e32 v1, v15, v1
	s_waitcnt lgkmcnt(4)
	v_mfma_f32_32x32x16_bf16 v[96:111], v[242:245], v[176:179], v[96:111]
	ds_read_b128 v[242:245], v233 offset:49280
	v_exp_f32_e32 v22, v137
	v_add_f32_e32 v1, v18, v1
	v_exp_f32_e32 v23, v138
	v_add_f32_e32 v1, v19, v1
	s_waitcnt lgkmcnt(4)
	v_mfma_f32_32x32x16_bf16 v[112:127], v[246:249], v[172:175], v[112:127]
	ds_read_b128 v[246:249], v233 offset:57472
	v_exp_f32_e32 v24, v139
	v_add_f32_e32 v1, v20, v1
	v_exp_f32_e32 v25, v140
	v_add_f32_e32 v1, v21, v1
	s_waitcnt lgkmcnt(4)
	v_mfma_f32_32x32x16_bf16 v[96:111], v[250:253], v[172:175], v[96:111]
	ds_read_b128 v[250:253], v254 offset:49280
	v_exp_f32_e32 v26, v141
	v_add_f32_e32 v1, v22, v1
	v_exp_f32_e32 v27, v142
	v_add_f32_e32 v1, v23, v1
	s_waitcnt lgkmcnt(4)
	v_mfma_f32_32x32x16_bf16 v[112:127], v[234:237], v[168:171], v[112:127]
	ds_read_b128 v[234:237], v254 offset:57472
	v_exp_f32_e32 v28, v143
	v_add_f32_e32 v1, v24, v1
	v_add_f32_e32 v1, v25, v1
	v_add_f32_e32 v1, v26, v1
	s_waitcnt lgkmcnt(4)
	v_mfma_f32_32x32x16_bf16 v[96:111], v[238:241], v[168:171], v[96:111]
	v_add_f32_e32 v1, v27, v1
	v_add_f32_e32 v1, v28, v1
	v_mov_b32_e32 v3, v1
	v_cvt_pk_bf16_f32 v4, v230, v232
	v_cvt_pk_bf16_f32 v5, v228, v231
	v_cvt_pk_bf16_f32 v6, v226, v229
	s_waitcnt lgkmcnt(3)
	v_mfma_f32_32x32x16_bf16 v[112:127], v[242:245], v[164:167], v[112:127]
	s_nop 1
	v_permlane32_swap_b32_e32 v1, v3
	v_cvt_pk_bf16_f32 v7, v225, v227
	v_permlane32_swap_b32_e32 v4, v6
	v_cvt_pk_bf16_f32 v8, v222, v224
	v_cvt_pk_bf16_f32 v9, v220, v223
	s_waitcnt lgkmcnt(2)
	v_mfma_f32_32x32x16_bf16 v[96:111], v[246:249], v[164:167], v[96:111]
	v_cvt_pk_bf16_f32 v10, v218, v221
	v_cvt_pk_bf16_f32 v11, v217, v219
	v_cvt_pk_bf16_f32 v12, v2, v12
	v_cvt_pk_bf16_f32 v13, v13, v14
	v_cvt_pk_bf16_f32 v14, v15, v18
	v_cvt_pk_bf16_f32 v15, v19, v20
	s_waitcnt lgkmcnt(1)
	v_mfma_f32_32x32x16_bf16 v[112:127], v[250:253], v[160:163], v[112:127]
	v_cvt_pk_bf16_f32 v18, v21, v22
	v_cvt_pk_bf16_f32 v19, v23, v24
	v_cvt_pk_bf16_f32 v20, v25, v26
	v_cvt_pk_bf16_f32 v21, v27, v28
	v_permlane32_swap_b32_e32 v5, v7
	s_waitcnt lgkmcnt(0)
	v_mfma_f32_32x32x16_bf16 v[96:111], v[234:237], v[160:163], v[96:111]
	v_permlane32_swap_b32_e32 v8, v10
	v_permlane32_swap_b32_e32 v9, v11
	v_permlane32_swap_b32_e32 v12, v14
	v_permlane32_swap_b32_e32 v13, v15
	v_permlane32_swap_b32_e32 v18, v20
	v_permlane32_swap_b32_e32 v19, v21
	s_setprio 0
	v_add_u32_e32 v2, s74, v206
	ds_read_b64_tr_b16 v[22:23], v2 offset:0
	ds_read_b64_tr_b16 v[24:25], v2 offset:0x800
	ds_read_b64_tr_b16 v[26:27], v2 offset:0x1000
	ds_read_b64_tr_b16 v[28:29], v2 offset:0x1800
	ds_read_b64_tr_b16 v[128:129], v2 offset:0x2000
	ds_read_b64_tr_b16 v[130:131], v2 offset:0x2800
	ds_read_b64_tr_b16 v[132:133], v2 offset:0x3000
	ds_read_b64_tr_b16 v[134:135], v2 offset:0x3800
	s_waitcnt lgkmcnt(0)
	s_nop 0
	v_mfma_f32_32x32x16_bf16 v[32:47], v[4:7], v[22:25], v[32:47]
	ds_read_b64_tr_b16 v[22:23], v2 offset:0x200
	ds_read_b64_tr_b16 v[24:25], v2 offset:0xa00
	v_mfma_f32_32x32x16_bf16 v[32:47], v[8:11], v[26:29], v[32:47]
	ds_read_b64_tr_b16 v[26:27], v2 offset:0x1200
	ds_read_b64_tr_b16 v[28:29], v2 offset:0x1a00
	v_mfma_f32_32x32x16_bf16 v[32:47], v[12:15], v[128:131], v[32:47]
	ds_read_b64_tr_b16 v[128:129], v2 offset:0x2200
	ds_read_b64_tr_b16 v[130:131], v2 offset:0x2a00
	v_mfma_f32_32x32x16_bf16 v[32:47], v[18:21], v[132:135], v[32:47]
	ds_read_b64_tr_b16 v[132:133], v2 offset:0x3200
	ds_read_b64_tr_b16 v[134:135], v2 offset:0x3a00
	s_waitcnt lgkmcnt(0)
	v_mfma_f32_32x32x16_bf16 v[48:63], v[4:7], v[22:25], v[48:63]
	ds_read_b64_tr_b16 v[22:23], v2 offset:0x400
	ds_read_b64_tr_b16 v[24:25], v2 offset:0xc00
	v_mfma_f32_32x32x16_bf16 v[48:63], v[8:11], v[26:29], v[48:63]
	ds_read_b64_tr_b16 v[26:27], v2 offset:0x1400
	ds_read_b64_tr_b16 v[28:29], v2 offset:0x1c00
	v_mfma_f32_32x32x16_bf16 v[48:63], v[12:15], v[128:131], v[48:63]
	ds_read_b64_tr_b16 v[128:129], v2 offset:0x2400
	ds_read_b64_tr_b16 v[130:131], v2 offset:0x2c00
	v_mfma_f32_32x32x16_bf16 v[48:63], v[18:21], v[132:135], v[48:63]
	ds_read_b64_tr_b16 v[132:133], v2 offset:0x3400
	ds_read_b64_tr_b16 v[134:135], v2 offset:0x3c00
	s_waitcnt lgkmcnt(0)
	v_mfma_f32_32x32x16_bf16 v[64:79], v[4:7], v[22:25], v[64:79]
	ds_read_b64_tr_b16 v[22:23], v2 offset:0x600
	ds_read_b64_tr_b16 v[24:25], v2 offset:0xe00
	v_mfma_f32_32x32x16_bf16 v[64:79], v[8:11], v[26:29], v[64:79]
	ds_read_b64_tr_b16 v[26:27], v2 offset:0x1600
	ds_read_b64_tr_b16 v[28:29], v2 offset:0x1e00
	v_mfma_f32_32x32x16_bf16 v[64:79], v[12:15], v[128:131], v[64:79]
	ds_read_b64_tr_b16 v[128:129], v2 offset:0x2600
	ds_read_b64_tr_b16 v[130:131], v2 offset:0x2e00
	v_mfma_f32_32x32x16_bf16 v[64:79], v[18:21], v[132:135], v[64:79]
	ds_read_b64_tr_b16 v[132:133], v2 offset:0x3600
	ds_read_b64_tr_b16 v[134:135], v2 offset:0x3e00
	s_waitcnt lgkmcnt(0)
	v_mfma_f32_32x32x16_bf16 v[80:95], v[4:7], v[22:25], v[80:95]
	v_max_f32_e32 v2, v113, v113
	v_max_f32_e32 v4, v112, v112
	v_max_f32_e32 v2, v4, v2
	v_max3_f32 v2, v2, v114, v115
	v_max3_f32 v2, v2, v116, v117
	v_max3_f32 v2, v2, v118, v119
	v_max3_f32 v2, v2, v120, v121
	v_max3_f32 v2, v2, v122, v123
	v_max3_f32 v2, v2, v124, v125
	v_max3_f32 v2, v2, v126, v127
	v_mfma_f32_32x32x16_bf16 v[80:95], v[8:11], v[26:29], v[80:95]
	v_max3_f32 v2, v2, v96, v97
	v_max3_f32 v2, v2, v98, v99
	v_max3_f32 v2, v2, v100, v101
	v_max3_f32 v2, v2, v102, v103
	v_max3_f32 v2, v2, v104, v105
	v_max3_f32 v2, v2, v106, v107
	v_max3_f32 v2, v2, v108, v109
	v_max3_f32 v2, v2, v110, v111
	v_mfma_f32_32x32x16_bf16 v[80:95], v[12:15], v[128:131], v[80:95]
	v_mov_b32_e32 v4, v2
	s_nop 1
	v_permlane32_swap_b32_e32 v2, v4
	v_max_f32_e32 v4, v4, v4
	v_max_f32_e32 v2, v2, v2
	v_max_f32_e32 v2, v2, v4
	v_sub_f32_e32 v4, v2, v214
	v_mul_f32_e32 v4, 0x3db504f3, v4
	v_cmp_ge_f32_e32 vcc, s84, v4
	v_max_f32_e32 v4, v214, v214
	v_max_f32_e32 v2, v4, v2
	v_mfma_f32_32x32x16_bf16 v[80:95], v[18:21], v[132:135], v[80:95]
	v_sub_f32_e32 v4, v214, v2
	v_mul_f32_e32 v4, 0x3e0293ee, v4
	v_exp_f32_e32 v4, v4
	s_cmp_eq_u64 vcc, exec
	s_cselect_b64 s[4:5], -1, 0
	v_cndmask_b32_e64 v4, v4, 1.0, s[4:5]
	v_cmp_gt_f32_e32 vcc, 1.0, v4
	s_cbranch_vccz .LBB0_313
	s_and_saveexec_b64 s[72:73], s[2:3]
	ds_write_b32 v204, v4 offset:128
	s_or_b64 exec, exec, s[72:73]
	s_waitcnt lgkmcnt(0)
	ds_read_b128 v[6:9], v203 offset:224
	ds_read_b128 v[10:13], v203 offset:192
	ds_read_b128 v[18:21], v203 offset:160
	ds_read_b128 v[22:25], v203 offset:128
	s_waitcnt lgkmcnt(3)
	v_pk_mul_f32 v[46:47], v[46:47], v[8:9]
	s_waitcnt lgkmcnt(2)
	v_pk_mul_f32 v[42:43], v[42:43], v[12:13]
	s_waitcnt lgkmcnt(1)
	v_pk_mul_f32 v[38:39], v[38:39], v[20:21]
	s_waitcnt lgkmcnt(0)
	v_pk_mul_f32 v[34:35], v[34:35], v[24:25]
	v_pk_mul_f32 v[44:45], v[44:45], v[6:7]
	v_pk_mul_f32 v[40:41], v[40:41], v[10:11]
	v_pk_mul_f32 v[36:37], v[36:37], v[18:19]
	v_pk_mul_f32 v[32:33], v[32:33], v[22:23]
	v_pk_mul_f32 v[62:63], v[62:63], v[8:9]
	v_pk_mul_f32 v[58:59], v[58:59], v[12:13]
	v_pk_mul_f32 v[54:55], v[54:55], v[20:21]
	v_pk_mul_f32 v[50:51], v[50:51], v[24:25]
	v_pk_mul_f32 v[60:61], v[60:61], v[6:7]
	v_pk_mul_f32 v[56:57], v[56:57], v[10:11]
	v_pk_mul_f32 v[52:53], v[52:53], v[18:19]
	v_pk_mul_f32 v[48:49], v[48:49], v[22:23]
	v_pk_mul_f32 v[78:79], v[78:79], v[8:9]
	v_pk_mul_f32 v[74:75], v[74:75], v[12:13]
	v_pk_mul_f32 v[70:71], v[70:71], v[20:21]
	v_pk_mul_f32 v[66:67], v[66:67], v[24:25]
	v_pk_mul_f32 v[76:77], v[76:77], v[6:7]
	v_pk_mul_f32 v[72:73], v[72:73], v[10:11]
	v_pk_mul_f32 v[68:69], v[68:69], v[18:19]
	v_pk_mul_f32 v[64:65], v[64:65], v[22:23]
	v_pk_mul_f32 v[94:95], v[94:95], v[8:9]
	v_pk_mul_f32 v[90:91], v[90:91], v[12:13]
	v_pk_mul_f32 v[86:87], v[86:87], v[20:21]
	v_pk_mul_f32 v[82:83], v[82:83], v[24:25]
	v_pk_mul_f32 v[92:93], v[92:93], v[6:7]
	v_pk_mul_f32 v[88:89], v[88:89], v[10:11]
	v_pk_mul_f32 v[84:85], v[84:85], v[18:19]
	v_pk_mul_f32 v[80:81], v[80:81], v[22:23]
.LBB0_313:
	v_cndmask_b32_e64 v2, v2, v214, s[4:5]
	s_waitcnt vmcnt(4) lgkmcnt(0)
	s_barrier
	v_add3_u32 v215, s69, v209, v208
	v_add3_u32 v216, s69, v210, v208
	v_add3_u32 v233, s69, v211, v208
	v_add3_u32 v254, s69, v212, v208
	ds_read_b128 v[234:237], v215 offset:49152
	ds_read_b128 v[238:241], v215 offset:57344
	ds_read_b128 v[242:245], v216 offset:49152
	ds_read_b128 v[246:249], v216 offset:57344
	ds_read_b128 v[250:253], v233 offset:49152
	s_add_i32 s4, s77, s42
	s_mov_b32 s5, m0
	s_mov_b32 m0, s4
	s_nop 0
	global_load_lds_dwordx4 v197, s[70:71]
	s_mov_b32 m0, s5
	s_addk_i32 s4, 0x400
	s_mov_b32 s5, m0
	s_mov_b32 m0, s4
	s_nop 0
	global_load_lds_dwordx4 v198, s[70:71]
	s_mov_b32 m0, s5
	s_add_u32 s4, s56, 0x4000
	s_addc_u32 s5, s57, 0
	s_add_i32 s72, s74, s97
	s_mov_b32 s73, m0
	s_mov_b32 m0, s72
	s_nop 0
	global_load_lds_dwordx4 v199, s[4:5]
	s_mov_b32 m0, s73
	s_addk_i32 s72, 0x400
	s_mov_b32 s73, m0
	s_mov_b32 m0, s72
	s_nop 0
	global_load_lds_dwordx4 v200, s[4:5]
	s_mov_b32 m0, s73
	v_mul_f32_e32 v5, 0xbe0293ee, v2
	v_fmamk_f32 v6, v112, 0x3e0293ee, v5
	v_fmamk_f32 v7, v113, 0x3e0293ee, v5
	v_fmamk_f32 v8, v114, 0x3e0293ee, v5
	v_fmamk_f32 v9, v115, 0x3e0293ee, v5
	v_fmamk_f32 v10, v116, 0x3e0293ee, v5
	v_fmamk_f32 v11, v117, 0x3e0293ee, v5
	v_fmamk_f32 v12, v118, 0x3e0293ee, v5
	v_fmamk_f32 v13, v119, 0x3e0293ee, v5
	v_fmamk_f32 v14, v120, 0x3e0293ee, v5
	v_fmamk_f32 v15, v121, 0x3e0293ee, v5
	v_fmamk_f32 v18, v122, 0x3e0293ee, v5
	v_fmamk_f32 v19, v123, 0x3e0293ee, v5
	v_fmamk_f32 v20, v124, 0x3e0293ee, v5
	v_fmamk_f32 v21, v125, 0x3e0293ee, v5
	v_fmamk_f32 v22, v126, 0x3e0293ee, v5
	v_fmamk_f32 v23, v127, 0x3e0293ee, v5
	v_fmamk_f32 v24, v96, 0x3e0293ee, v5
	v_fmamk_f32 v25, v97, 0x3e0293ee, v5
	v_fmamk_f32 v26, v98, 0x3e0293ee, v5
	v_fmamk_f32 v27, v99, 0x3e0293ee, v5
	v_fmamk_f32 v28, v100, 0x3e0293ee, v5
	v_fmamk_f32 v29, v101, 0x3e0293ee, v5
	v_fmamk_f32 v30, v102, 0x3e0293ee, v5
	v_fmamk_f32 v31, v103, 0x3e0293ee, v5
	v_fmamk_f32 v128, v104, 0x3e0293ee, v5
	v_fmamk_f32 v129, v105, 0x3e0293ee, v5
	v_fmamk_f32 v130, v106, 0x3e0293ee, v5
	v_fmamk_f32 v131, v107, 0x3e0293ee, v5
	v_fmamk_f32 v132, v108, 0x3e0293ee, v5
	v_fmamk_f32 v133, v109, 0x3e0293ee, v5
	v_fmamk_f32 v134, v110, 0x3e0293ee, v5
	v_fmac_f32_e32 v5, 0x3e0293ee, v111
	s_setprio 1
	s_waitcnt lgkmcnt(4)
	v_mfma_f32_32x32x16_bf16 v[112:127], v[234:237], v[188:191], 0
	ds_read_b128 v[234:237], v233 offset:57344
	v_exp_f32_e32 v135, v6
	v_exp_f32_e32 v136, v7
	v_exp_f32_e32 v137, v8
	v_exp_f32_e32 v138, v9
	s_waitcnt lgkmcnt(4)
	v_mfma_f32_32x32x16_bf16 v[96:111], v[238:241], v[188:191], 0
	ds_read_b128 v[238:241], v254 offset:49152
	v_exp_f32_e32 v10, v10
	v_exp_f32_e32 v11, v11
	v_exp_f32_e32 v12, v12
	v_exp_f32_e32 v13, v13
	s_waitcnt lgkmcnt(4)
	v_mfma_f32_32x32x16_bf16 v[112:127], v[242:245], v[184:187], v[112:127]
	ds_read_b128 v[242:245], v254 offset:57344
	v_exp_f32_e32 v14, v14
	v_exp_f32_e32 v15, v15
	v_exp_f32_e32 v18, v18
	s_waitcnt lgkmcnt(4)
	v_mfma_f32_32x32x16_bf16 v[96:111], v[246:249], v[184:187], v[96:111]
	ds_read_b128 v[246:249], v215 offset:49280
	v_exp_f32_e32 v19, v19
	v_exp_f32_e32 v20, v20
	v_exp_f32_e32 v21, v21
	v_exp_f32_e32 v22, v22
	s_waitcnt lgkmcnt(4)
	v_mfma_f32_32x32x16_bf16 v[112:127], v[250:253], v[180:183], v[112:127]
	ds_read_b128 v[250:253], v215 offset:57472
	v_exp_f32_e32 v23, v23
	v_exp_f32_e32 v7, v24
	v_exp_f32_e32 v24, v25
	v_exp_f32_e32 v25, v26
	s_waitcnt lgkmcnt(4)
	v_mfma_f32_32x32x16_bf16 v[96:111], v[234:237], v[180:183], v[96:111]
	ds_read_b128 v[234:237], v216 offset:49280
	v_exp_f32_e32 v26, v27
	v_exp_f32_e32 v27, v28
	v_exp_f32_e32 v28, v29
	v_exp_f32_e32 v29, v30
	s_waitcnt lgkmcnt(4)
	v_mfma_f32_32x32x16_bf16 v[112:127], v[238:241], v[176:179], v[112:127]
	ds_read_b128 v[238:241], v216 offset:57472
	v_exp_f32_e32 v30, v31
	v_exp_f32_e32 v31, v128
	v_exp_f32_e32 v128, v129
	v_exp_f32_e32 v129, v130
	s_waitcnt lgkmcnt(4)
	v_mfma_f32_32x32x16_bf16 v[96:111], v[242:245], v[176:179], v[96:111]
	ds_read_b128 v[242:245], v233 offset:49280
	v_exp_f32_e32 v130, v131
	v_exp_f32_e32 v131, v132
	v_exp_f32_e32 v132, v133
	v_exp_f32_e32 v133, v134
	s_waitcnt lgkmcnt(4)
	v_mfma_f32_32x32x16_bf16 v[112:127], v[246:249], v[172:175], v[112:127]
	ds_read_b128 v[246:249], v233 offset:57472
	v_exp_f32_e32 v134, v5
	v_add_f32_e32 v5, 0, v135
	v_add_f32_e32 v5, v136, v5
	v_add_f32_e32 v5, v137, v5
	v_add_f32_e32 v5, v138, v5
	v_add_f32_e32 v5, v10, v5
	s_waitcnt lgkmcnt(4)
	v_mfma_f32_32x32x16_bf16 v[96:111], v[250:253], v[172:175], v[96:111]
	ds_read_b128 v[250:253], v254 offset:49280
	v_add_f32_e32 v5, v11, v5
	v_add_f32_e32 v5, v12, v5
	v_add_f32_e32 v5, v13, v5
	v_add_f32_e32 v5, v14, v5
	v_add_f32_e32 v5, v15, v5
	v_add_f32_e32 v5, v18, v5
	v_add_f32_e32 v5, v19, v5
	v_add_f32_e32 v5, v20, v5
	s_waitcnt lgkmcnt(4)
	v_mfma_f32_32x32x16_bf16 v[112:127], v[234:237], v[168:171], v[112:127]
	ds_read_b128 v[234:237], v254 offset:57472
	v_add_f32_e32 v5, v21, v5
	v_add_f32_e32 v5, v22, v5
	v_add_f32_e32 v5, v23, v5
	v_add_f32_e32 v5, v7, v5
	v_add_f32_e32 v5, v24, v5
	v_add_f32_e32 v5, v25, v5
	v_add_f32_e32 v5, v26, v5
	s_waitcnt lgkmcnt(4)
	v_mfma_f32_32x32x16_bf16 v[96:111], v[238:241], v[168:171], v[96:111]
	v_add_f32_e32 v5, v27, v5
	v_add_f32_e32 v5, v28, v5
	v_add_f32_e32 v5, v29, v5
	v_add_f32_e32 v5, v30, v5
	v_add_f32_e32 v5, v31, v5
	v_add_f32_e32 v5, v128, v5
	v_add_f32_e32 v5, v129, v5
	v_add_f32_e32 v5, v130, v5
	s_waitcnt lgkmcnt(3)
	v_mfma_f32_32x32x16_bf16 v[112:127], v[242:245], v[164:167], v[112:127]
	v_add_f32_e32 v5, v131, v5
	v_add_f32_e32 v5, v132, v5
	v_add_f32_e32 v5, v133, v5
	v_add_f32_e32 v5, v134, v5
	v_mov_b32_e32 v6, v5
	v_cvt_pk_bf16_f32 v8, v135, v136
	v_cvt_pk_bf16_f32 v9, v137, v138
	v_cvt_pk_bf16_f32 v10, v10, v11
	s_waitcnt lgkmcnt(2)
	v_mfma_f32_32x32x16_bf16 v[96:111], v[246:249], v[164:167], v[96:111]
	s_nop 1
	v_permlane32_swap_b32_e32 v5, v6
	v_cvt_pk_bf16_f32 v11, v12, v13
	v_permlane32_swap_b32_e32 v8, v10
	v_cvt_pk_bf16_f32 v12, v14, v15
	v_cvt_pk_bf16_f32 v13, v18, v19
	v_cvt_pk_bf16_f32 v14, v20, v21
	v_cvt_pk_bf16_f32 v15, v22, v23
	s_waitcnt lgkmcnt(1)
	v_mfma_f32_32x32x16_bf16 v[112:127], v[250:253], v[160:163], v[112:127]
	v_cvt_pk_bf16_f32 v18, v7, v24
	v_cvt_pk_bf16_f32 v19, v25, v26
	v_cvt_pk_bf16_f32 v20, v27, v28
	v_cvt_pk_bf16_f32 v21, v29, v30
	v_cvt_pk_bf16_f32 v22, v31, v128
	v_cvt_pk_bf16_f32 v23, v129, v130
	v_cvt_pk_bf16_f32 v24, v131, v132
	s_waitcnt lgkmcnt(0)
	v_mfma_f32_32x32x16_bf16 v[96:111], v[234:237], v[160:163], v[96:111]
	v_cvt_pk_bf16_f32 v25, v133, v134
	v_permlane32_swap_b32_e32 v9, v11
	v_permlane32_swap_b32_e32 v12, v14
	v_permlane32_swap_b32_e32 v13, v15
	v_permlane32_swap_b32_e32 v18, v20
	v_permlane32_swap_b32_e32 v19, v21
	v_permlane32_swap_b32_e32 v22, v24
	v_permlane32_swap_b32_e32 v23, v25
	s_setprio 0
	v_add_u32_e32 v7, s77, v206
	ds_read_b64_tr_b16 v[26:27], v7 offset:0
	ds_read_b64_tr_b16 v[28:29], v7 offset:0x800
	ds_read_b64_tr_b16 v[128:129], v7 offset:0x1000
	ds_read_b64_tr_b16 v[130:131], v7 offset:0x1800
	ds_read_b64_tr_b16 v[132:133], v7 offset:0x2000
	ds_read_b64_tr_b16 v[134:135], v7 offset:0x2800
	ds_read_b64_tr_b16 v[136:137], v7 offset:0x3000
	ds_read_b64_tr_b16 v[138:139], v7 offset:0x3800
	s_waitcnt lgkmcnt(0)
	s_nop 0
	v_mfma_f32_32x32x16_bf16 v[32:47], v[8:11], v[26:29], v[32:47]
	ds_read_b64_tr_b16 v[26:27], v7 offset:0x200
	ds_read_b64_tr_b16 v[28:29], v7 offset:0xa00
	v_mfma_f32_32x32x16_bf16 v[32:47], v[12:15], v[128:131], v[32:47]
	ds_read_b64_tr_b16 v[128:129], v7 offset:0x1200
	ds_read_b64_tr_b16 v[130:131], v7 offset:0x1a00
	v_mfma_f32_32x32x16_bf16 v[32:47], v[18:21], v[132:135], v[32:47]
	ds_read_b64_tr_b16 v[132:133], v7 offset:0x2200
	ds_read_b64_tr_b16 v[134:135], v7 offset:0x2a00
	v_mfma_f32_32x32x16_bf16 v[32:47], v[22:25], v[136:139], v[32:47]
	ds_read_b64_tr_b16 v[136:137], v7 offset:0x3200
	ds_read_b64_tr_b16 v[138:139], v7 offset:0x3a00
	s_waitcnt lgkmcnt(0)
	v_mfma_f32_32x32x16_bf16 v[48:63], v[8:11], v[26:29], v[48:63]
	ds_read_b64_tr_b16 v[26:27], v7 offset:0x400
	ds_read_b64_tr_b16 v[28:29], v7 offset:0xc00
	v_mfma_f32_32x32x16_bf16 v[48:63], v[12:15], v[128:131], v[48:63]
	ds_read_b64_tr_b16 v[128:129], v7 offset:0x1400
	ds_read_b64_tr_b16 v[130:131], v7 offset:0x1c00
	v_mfma_f32_32x32x16_bf16 v[48:63], v[18:21], v[132:135], v[48:63]
	ds_read_b64_tr_b16 v[132:133], v7 offset:0x2400
	ds_read_b64_tr_b16 v[134:135], v7 offset:0x2c00
	v_mfma_f32_32x32x16_bf16 v[48:63], v[22:25], v[136:139], v[48:63]
	ds_read_b64_tr_b16 v[136:137], v7 offset:0x3400
	ds_read_b64_tr_b16 v[138:139], v7 offset:0x3c00
	s_waitcnt lgkmcnt(0)
	v_mfma_f32_32x32x16_bf16 v[64:79], v[8:11], v[26:29], v[64:79]
	ds_read_b64_tr_b16 v[26:27], v7 offset:0x600
	ds_read_b64_tr_b16 v[28:29], v7 offset:0xe00
	v_mfma_f32_32x32x16_bf16 v[64:79], v[12:15], v[128:131], v[64:79]
	ds_read_b64_tr_b16 v[128:129], v7 offset:0x1600
	ds_read_b64_tr_b16 v[130:131], v7 offset:0x1e00
	v_mfma_f32_32x32x16_bf16 v[64:79], v[18:21], v[132:135], v[64:79]
	ds_read_b64_tr_b16 v[132:133], v7 offset:0x2600
	ds_read_b64_tr_b16 v[134:135], v7 offset:0x2e00
	v_mfma_f32_32x32x16_bf16 v[64:79], v[22:25], v[136:139], v[64:79]
	ds_read_b64_tr_b16 v[136:137], v7 offset:0x3600
	ds_read_b64_tr_b16 v[138:139], v7 offset:0x3e00
	s_waitcnt lgkmcnt(0)
	v_mfma_f32_32x32x16_bf16 v[80:95], v[8:11], v[26:29], v[80:95]
	v_max_f32_e32 v7, v113, v113
	v_max_f32_e32 v8, v112, v112
	v_max_f32_e32 v7, v8, v7
	v_max3_f32 v7, v7, v114, v115
	v_max3_f32 v7, v7, v116, v117
	v_max3_f32 v7, v7, v118, v119
	v_max3_f32 v7, v7, v120, v121
	v_max3_f32 v7, v7, v122, v123
	v_max3_f32 v7, v7, v124, v125
	v_max3_f32 v7, v7, v126, v127
	v_mfma_f32_32x32x16_bf16 v[80:95], v[12:15], v[128:131], v[80:95]
	v_max3_f32 v7, v7, v96, v97
	v_max3_f32 v7, v7, v98, v99
	v_max3_f32 v7, v7, v100, v101
	v_max3_f32 v7, v7, v102, v103
	v_max3_f32 v7, v7, v104, v105
	v_max3_f32 v7, v7, v106, v107
	v_max3_f32 v7, v7, v108, v109
	v_max3_f32 v7, v7, v110, v111
	v_mfma_f32_32x32x16_bf16 v[80:95], v[18:21], v[132:135], v[80:95]
	v_mov_b32_e32 v8, v7
	s_nop 1
	v_permlane32_swap_b32_e32 v7, v8
	v_max_f32_e32 v8, v8, v8
	v_max_f32_e32 v7, v7, v7
	v_max_f32_e32 v7, v7, v8
	v_sub_f32_e32 v8, v7, v2
	v_mul_f32_e32 v8, 0x3db504f3, v8
	v_cmp_ge_f32_e32 vcc, s84, v8
	v_max_f32_e32 v8, v2, v2
	v_max_f32_e32 v8, v8, v7
	v_mfma_f32_32x32x16_bf16 v[80:95], v[22:25], v[136:139], v[80:95]
	v_sub_f32_e32 v7, v2, v8
	v_mul_f32_e32 v7, 0x3e0293ee, v7
	v_exp_f32_e32 v7, v7
	s_cmp_eq_u64 vcc, exec
	s_cselect_b64 s[4:5], -1, 0
	v_cndmask_b32_e64 v7, v7, 1.0, s[4:5]
	v_cmp_gt_f32_e32 vcc, 1.0, v7
	s_cbranch_vccz .LBB0_317
	s_and_saveexec_b64 s[72:73], s[2:3]
	ds_write_b32 v204, v7 offset:128
	s_or_b64 exec, exec, s[72:73]
	s_waitcnt lgkmcnt(0)
	ds_read_b128 v[10:13], v203 offset:224
	ds_read_b128 v[18:21], v203 offset:192
	ds_read_b128 v[22:25], v203 offset:160
	ds_read_b128 v[26:29], v203 offset:128
	s_waitcnt lgkmcnt(3)
	v_pk_mul_f32 v[46:47], v[46:47], v[12:13]
	s_waitcnt lgkmcnt(2)
	v_pk_mul_f32 v[42:43], v[42:43], v[20:21]
	s_waitcnt lgkmcnt(1)
	v_pk_mul_f32 v[38:39], v[38:39], v[24:25]
	s_waitcnt lgkmcnt(0)
	v_pk_mul_f32 v[34:35], v[34:35], v[28:29]
	v_pk_mul_f32 v[44:45], v[44:45], v[10:11]
	v_pk_mul_f32 v[40:41], v[40:41], v[18:19]
	v_pk_mul_f32 v[36:37], v[36:37], v[22:23]
	v_pk_mul_f32 v[32:33], v[32:33], v[26:27]
	v_pk_mul_f32 v[62:63], v[62:63], v[12:13]
	v_pk_mul_f32 v[58:59], v[58:59], v[20:21]
	v_pk_mul_f32 v[54:55], v[54:55], v[24:25]
	v_pk_mul_f32 v[50:51], v[50:51], v[28:29]
	v_pk_mul_f32 v[60:61], v[60:61], v[10:11]
	v_pk_mul_f32 v[56:57], v[56:57], v[18:19]
	v_pk_mul_f32 v[52:53], v[52:53], v[22:23]
	v_pk_mul_f32 v[48:49], v[48:49], v[26:27]
	v_pk_mul_f32 v[78:79], v[78:79], v[12:13]
	v_pk_mul_f32 v[74:75], v[74:75], v[20:21]
	v_pk_mul_f32 v[70:71], v[70:71], v[24:25]
	v_pk_mul_f32 v[66:67], v[66:67], v[28:29]
	v_pk_mul_f32 v[76:77], v[76:77], v[10:11]
	v_pk_mul_f32 v[72:73], v[72:73], v[18:19]
	v_pk_mul_f32 v[68:69], v[68:69], v[22:23]
	v_pk_mul_f32 v[64:65], v[64:65], v[26:27]
	v_pk_mul_f32 v[94:95], v[94:95], v[12:13]
	v_pk_mul_f32 v[90:91], v[90:91], v[20:21]
	v_pk_mul_f32 v[86:87], v[86:87], v[24:25]
	v_pk_mul_f32 v[82:83], v[82:83], v[28:29]
	v_pk_mul_f32 v[92:93], v[92:93], v[10:11]
	v_pk_mul_f32 v[88:89], v[88:89], v[18:19]
	v_pk_mul_f32 v[84:85], v[84:85], v[22:23]
	v_pk_mul_f32 v[80:81], v[80:81], v[26:27]
